# nt (non-temporal) policy on the prologue's once-read x rows and f32 weight loads, on top of 2a fast-path loads
# speedup vs baseline: 1.0197x; 1.0197x over previous
.LBB0_17:
	s_lshl_b32 s14, s6, 1
	s_lshl_b32 s15, s2, 1
	v_or_b32_e32 v4, s15, v18
	s_add_i32 s16, s14, 4
	s_add_i32 s17, s15, 4
	v_mov_b32_e32 v27, v5
	s_add_i32 s19, s15, 8
	v_lshlrev_b64 v[40:41], 12, v[4:5]
	v_or_b32_e32 v26, s16, v3
	v_or_b32_e32 v4, s17, v18
	v_mov_b32_e32 v25, v5
	v_or_b32_e32 v24, s14, v3
	s_add_i32 s21, s15, 12
	v_lshlrev_b64 v[26:27], 12, v[26:27]
	v_lshlrev_b64 v[42:43], 12, v[4:5]
	v_or_b32_e32 v4, s19, v18
	s_add_i32 s18, s14, 8
	s_add_i32 s20, s14, 12
	s_add_i32 s23, s15, 16
	v_lshlrev_b64 v[24:25], 12, v[24:25]
	v_lshl_add_u64 v[40:41], v[16:17], 0, v[40:41]
	v_lshl_add_u64 v[26:27], v[16:17], 0, v[26:27]
	v_lshlrev_b64 v[44:45], 12, v[4:5]
	v_or_b32_e32 v4, s21, v18
	v_mov_b32_e32 v29, v5
	v_mov_b32_e32 v31, v5
	s_add_i32 s25, s15, 20
	v_or_b32_e32 v28, s18, v3
	v_or_b32_e32 v30, s20, v3
	v_lshl_add_u64 v[24:25], v[16:17], 0, v[24:25]
	v_lshl_add_u64 v[42:43], v[16:17], 0, v[42:43]
	global_load_dword v23, v[40:41], off nt
	global_load_dword v56, v[24:25], off nt
	global_load_dword v57, v[42:43], off nt
	global_load_dword v58, v[26:27], off nt
	v_lshlrev_b64 v[26:27], 12, v[4:5]
	v_or_b32_e32 v4, s23, v18
	s_add_i32 s22, s14, 16
	s_add_i32 s24, s14, 20
	s_add_i32 s27, s15, 24
	v_lshlrev_b64 v[28:29], 12, v[28:29]
	v_lshlrev_b64 v[30:31], 12, v[30:31]
	v_lshl_add_u64 v[24:25], v[16:17], 0, v[44:45]
	v_lshl_add_u64 v[26:27], v[16:17], 0, v[26:27]
	v_lshlrev_b64 v[40:41], 12, v[4:5]
	v_or_b32_e32 v4, s25, v18
	v_mov_b32_e32 v33, v5
	v_mov_b32_e32 v35, v5
	s_add_i32 s26, s14, 24
	s_add_i32 s28, s14, 28
	s_add_i32 s29, s15, 28
	v_or_b32_e32 v32, s22, v3
	v_or_b32_e32 v34, s24, v3
	v_lshl_add_u64 v[28:29], v[16:17], 0, v[28:29]
	v_lshl_add_u64 v[30:31], v[16:17], 0, v[30:31]
	global_load_dword v59, v[24:25], off nt
	global_load_dword v60, v[28:29], off nt
	global_load_dword v61, v[26:27], off nt
	global_load_dword v62, v[30:31], off nt
	v_lshlrev_b64 v[26:27], 12, v[4:5]
	v_or_b32_e32 v4, s27, v18
	v_mov_b32_e32 v37, v5
	v_mov_b32_e32 v39, v5
	v_or_b32_e32 v36, s26, v3
	v_or_b32_e32 v38, s28, v3
	v_lshlrev_b64 v[32:33], 12, v[32:33]
	v_lshlrev_b64 v[34:35], 12, v[34:35]
	v_lshl_add_u64 v[24:25], v[16:17], 0, v[40:41]
	v_lshl_add_u64 v[26:27], v[16:17], 0, v[26:27]
	v_lshlrev_b64 v[28:29], 12, v[4:5]
	v_or_b32_e32 v4, s29, v18
	v_lshlrev_b64 v[36:37], 12, v[36:37]
	v_lshlrev_b64 v[38:39], 12, v[38:39]
	v_lshl_add_u64 v[32:33], v[16:17], 0, v[32:33]
	v_lshl_add_u64 v[34:35], v[16:17], 0, v[34:35]
	global_load_dword v63, v[24:25], off nt
	global_load_dword v64, v[32:33], off nt
	global_load_dword v65, v[26:27], off nt
	global_load_dword v66, v[34:35], off nt
	v_lshl_add_u64 v[24:25], v[16:17], 0, v[28:29]
	v_lshlrev_b64 v[26:27], 12, v[4:5]
	v_lshl_add_u64 v[36:37], v[16:17], 0, v[36:37]
	v_lshl_add_u64 v[38:39], v[16:17], 0, v[38:39]
	v_lshl_add_u64 v[26:27], v[16:17], 0, v[26:27]
	global_load_dword v4, v[24:25], off nt
	global_load_dword v67, v[36:37], off nt
	global_load_dword v68, v[26:27], off nt
	global_load_dword v69, v[38:39], off nt
	v_or_b32_e32 v26, s14, v1
	v_or_b32_e32 v24, s15, v2
	s_add_i32 s2, s2, 16
	s_add_i32 s6, s6, 16
	s_add_i32 s7, s7, -16
	v_mad_u64_u32 v[24:25], s[14:15], v24, s8, v[8:9]
	v_mad_u64_u32 v[26:27], s[14:15], v26, s8, v[8:9]
	v_or_b32_e32 v25, s16, v1
	v_or_b32_e32 v27, s17, v2
	v_or_b32_e32 v34, s18, v1
	v_or_b32_e32 v32, s19, v2
	v_or_b32_e32 v38, s20, v1
	v_or_b32_e32 v36, s21, v2
	v_or_b32_e32 v42, s22, v1
	v_or_b32_e32 v40, s23, v2
	v_or_b32_e32 v46, s24, v1
	v_or_b32_e32 v44, s25, v2
	v_or_b32_e32 v50, s26, v1
	v_or_b32_e32 v48, s27, v2
	v_or_b32_e32 v54, s28, v1
	v_or_b32_e32 v52, s29, v2
	s_cmp_lg_u32 s7, 0
	v_mad_u64_u32 v[28:29], s[14:15], v27, s8, v[8:9]
	v_mad_u64_u32 v[30:31], s[14:15], v25, s8, v[8:9]
	v_mad_u64_u32 v[32:33], s[14:15], v32, s8, v[8:9]
	v_mad_u64_u32 v[34:35], s[14:15], v34, s8, v[8:9]
	v_mad_u64_u32 v[36:37], s[14:15], v36, s8, v[8:9]
	v_mad_u64_u32 v[38:39], s[14:15], v38, s8, v[8:9]
	v_mad_u64_u32 v[40:41], s[14:15], v40, s8, v[8:9]
	v_mad_u64_u32 v[42:43], s[14:15], v42, s8, v[8:9]
	v_mad_u64_u32 v[44:45], s[14:15], v44, s8, v[8:9]
	v_mad_u64_u32 v[46:47], s[14:15], v46, s8, v[8:9]
	v_mad_u64_u32 v[48:49], s[14:15], v48, s8, v[8:9]
	v_mad_u64_u32 v[50:51], s[14:15], v50, s8, v[8:9]
	v_mad_u64_u32 v[52:53], s[14:15], v52, s8, v[8:9]
	v_mad_u64_u32 v[54:55], s[14:15], v54, s8, v[8:9]
	s_waitcnt vmcnt(15)
	ds_write_b32 v24, v23
	s_waitcnt vmcnt(14)
	ds_write_b32 v26, v56
	s_waitcnt vmcnt(13)
	ds_write_b32 v28, v57
	s_waitcnt vmcnt(12)
	ds_write_b32 v30, v58
	s_waitcnt vmcnt(11)
	ds_write_b32 v32, v59
	s_waitcnt vmcnt(10)
	ds_write_b32 v34, v60
	s_waitcnt vmcnt(9)
	ds_write_b32 v36, v61
	s_waitcnt vmcnt(8)
	ds_write_b32 v38, v62
	s_waitcnt vmcnt(7)
	ds_write_b32 v40, v63
	s_waitcnt vmcnt(6)
	ds_write_b32 v42, v64
	s_waitcnt vmcnt(5)
	ds_write_b32 v44, v65
	s_waitcnt vmcnt(4)
	ds_write_b32 v46, v66
	s_waitcnt vmcnt(3)
	ds_write_b32 v48, v4
	s_waitcnt vmcnt(2)
	ds_write_b32 v50, v67
	s_waitcnt vmcnt(1)
	ds_write_b32 v52, v68
	s_waitcnt vmcnt(0)
	ds_write_b32 v54, v69
	s_cbranch_scc1 .LBB0_17
	s_waitcnt lgkmcnt(0)
	ds_read2_b32 v[16:17], v19 offset1:8
	ds_read2_b32 v[30:31], v19 offset0:33 offset1:41
	ds_read2_b32 v[32:33], v19 offset0:66 offset1:74
	ds_read2_b32 v[34:35], v19 offset0:99 offset1:107
	ds_read2_b32 v[36:37], v19 offset0:132 offset1:140
	ds_read2_b32 v[38:39], v19 offset0:165 offset1:173
	s_waitcnt lgkmcnt(5)
	v_bfe_u32 v3, v16, 16, 1
	v_add3_u32 v3, v16, v3, s9
	s_waitcnt lgkmcnt(4)
	v_bfe_u32 v4, v30, 16, 1
	v_lshrrev_b32_e32 v3, 16, v3
	v_add3_u32 v4, v30, v4, s9
	v_and_or_b32 v24, v4, s11, v3
	s_waitcnt lgkmcnt(3)
	v_bfe_u32 v3, v32, 16, 1
	v_add3_u32 v3, v32, v3, s9
	s_waitcnt lgkmcnt(2)
	v_bfe_u32 v4, v34, 16, 1
	ds_read2_b32 v[40:41], v19 offset0:198 offset1:206
	v_lshrrev_b32_e32 v3, 16, v3
	v_add3_u32 v4, v34, v4, s9
	ds_read2_b32 v[42:43], v19 offset0:231 offset1:239
	v_and_or_b32 v25, v4, s11, v3
	s_waitcnt lgkmcnt(3)
	v_bfe_u32 v3, v36, 16, 1
	v_add3_u32 v3, v36, v3, s9
	s_waitcnt lgkmcnt(2)
	v_bfe_u32 v4, v38, 16, 1
	v_lshrrev_b32_e32 v3, 16, v3
	v_add3_u32 v4, v38, v4, s9
	v_and_or_b32 v26, v4, s11, v3
	s_waitcnt lgkmcnt(1)
	v_bfe_u32 v3, v40, 16, 1
	v_add3_u32 v3, v40, v3, s9
	s_waitcnt lgkmcnt(0)
	v_bfe_u32 v4, v42, 16, 1
	v_lshrrev_b32_e32 v3, 16, v3
	v_add3_u32 v4, v42, v4, s9
	s_lshl_b32 s2, s5, 1
	v_and_or_b32 v27, v4, s11, v3
	v_or_b32_e32 v3, s4, v9
	v_lshl_add_u64 v[28:29], v[10:11], 0, s[2:3]
	v_lshlrev_b32_e32 v4, 11, v3
	v_bfe_u32 v3, v17, 16, 1
	v_lshl_add_u64 v[44:45], v[28:29], 0, v[4:5]
	v_add3_u32 v3, v17, v3, s9
	v_bfe_u32 v4, v31, 16, 1
	v_lshrrev_b32_e32 v3, 16, v3
	v_add3_u32 v4, v31, v4, s9
	global_store_dwordx4 v[44:45], v[24:27], off
	ds_read2_b32 v[16:17], v19 offset0:16 offset1:24
	s_nop 0
	v_and_or_b32 v24, v4, s11, v3
	v_bfe_u32 v3, v33, 16, 1
	v_add3_u32 v3, v33, v3, s9
	v_bfe_u32 v4, v35, 16, 1
	v_lshrrev_b32_e32 v3, 16, v3
	v_add3_u32 v4, v35, v4, s9
	v_and_or_b32 v25, v4, s11, v3
	v_bfe_u32 v3, v37, 16, 1
	v_add3_u32 v3, v37, v3, s9
	v_bfe_u32 v4, v39, 16, 1
	v_lshrrev_b32_e32 v3, 16, v3
	v_add3_u32 v4, v39, v4, s9
	v_and_or_b32 v26, v4, s11, v3
	v_bfe_u32 v3, v41, 16, 1
	v_add3_u32 v3, v41, v3, s9
	v_bfe_u32 v4, v43, 16, 1
	v_lshrrev_b32_e32 v3, 16, v3
	v_add3_u32 v4, v43, v4, s9
	v_and_or_b32 v27, v4, s11, v3
	v_or_b32_e32 v3, s4, v20
	v_lshlrev_b32_e32 v4, 11, v3
	v_lshl_add_u64 v[30:31], v[28:29], 0, v[4:5]
	global_store_dwordx4 v[30:31], v[24:27], off
	ds_read2_b32 v[30:31], v19 offset0:49 offset1:57
	ds_read2_b32 v[32:33], v19 offset0:82 offset1:90
	ds_read2_b32 v[34:35], v19 offset0:115 offset1:123
	s_waitcnt lgkmcnt(3)
	v_bfe_u32 v3, v16, 16, 1
	v_add3_u32 v3, v16, v3, s9
	s_waitcnt lgkmcnt(2)
	v_bfe_u32 v4, v30, 16, 1
	ds_read2_b32 v[36:37], v19 offset0:148 offset1:156
	v_lshrrev_b32_e32 v3, 16, v3
	v_add3_u32 v4, v30, v4, s9
	ds_read2_b32 v[38:39], v19 offset0:181 offset1:189
	v_and_or_b32 v24, v4, s11, v3
	s_waitcnt lgkmcnt(3)
	v_bfe_u32 v3, v32, 16, 1
	v_add3_u32 v3, v32, v3, s9
	s_waitcnt lgkmcnt(2)
	v_bfe_u32 v4, v34, 16, 1
	ds_read2_b32 v[40:41], v19 offset0:214 offset1:222
	v_lshrrev_b32_e32 v3, 16, v3
	v_add3_u32 v4, v34, v4, s9
	ds_read2_b32 v[42:43], v19 offset0:247 offset1:255
	v_and_or_b32 v25, v4, s11, v3
	s_waitcnt lgkmcnt(3)
	v_bfe_u32 v3, v36, 16, 1
	v_add3_u32 v3, v36, v3, s9
	s_waitcnt lgkmcnt(2)
	v_bfe_u32 v4, v38, 16, 1
	v_lshrrev_b32_e32 v3, 16, v3
	v_add3_u32 v4, v38, v4, s9
	v_and_or_b32 v26, v4, s11, v3
	s_waitcnt lgkmcnt(1)
	v_bfe_u32 v3, v40, 16, 1
	v_add3_u32 v3, v40, v3, s9
	s_waitcnt lgkmcnt(0)
	v_bfe_u32 v4, v42, 16, 1
	v_lshrrev_b32_e32 v3, 16, v3
	v_add3_u32 v4, v42, v4, s9
	v_and_or_b32 v27, v4, s11, v3
	v_or_b32_e32 v3, s4, v21
	v_lshlrev_b32_e32 v4, 11, v3
	v_bfe_u32 v3, v17, 16, 1
	v_lshl_add_u64 v[44:45], v[28:29], 0, v[4:5]
	v_add3_u32 v3, v17, v3, s9
	v_bfe_u32 v4, v31, 16, 1
	v_lshrrev_b32_e32 v3, 16, v3
	v_add3_u32 v4, v31, v4, s9
	global_store_dwordx4 v[44:45], v[24:27], off
	s_nop 1
	v_and_or_b32 v24, v4, s11, v3
	v_bfe_u32 v3, v33, 16, 1
	v_add3_u32 v3, v33, v3, s9
	v_bfe_u32 v4, v35, 16, 1
	v_lshrrev_b32_e32 v3, 16, v3
	v_add3_u32 v4, v35, v4, s9
	v_and_or_b32 v25, v4, s11, v3
	v_bfe_u32 v3, v37, 16, 1
	v_add3_u32 v3, v37, v3, s9
	v_bfe_u32 v4, v39, 16, 1
	v_lshrrev_b32_e32 v3, 16, v3
	v_add3_u32 v4, v39, v4, s9
	v_and_or_b32 v26, v4, s11, v3
	v_bfe_u32 v3, v41, 16, 1
	v_add3_u32 v3, v41, v3, s9
	v_bfe_u32 v4, v43, 16, 1
	v_lshrrev_b32_e32 v3, 16, v3
	v_add3_u32 v4, v43, v4, s9
	v_and_or_b32 v27, v4, s11, v3
	v_or_b32_e32 v3, s4, v22
	v_lshlrev_b32_e32 v4, 11, v3
	v_lshl_add_u64 v[16:17], v[28:29], 0, v[4:5]
	global_store_dwordx4 v[16:17], v[24:27], off
	s_waitcnt lgkmcnt(0)
	s_branch .LBB0_14

.LBB0_21:
	s_lshl_b32 s16, s2, 1
	s_lshl_b32 s17, s5, 1
	v_or_b32_e32 v18, s16, v3
	v_or_b32_e32 v23, s17, v4
	s_add_i32 s18, s16, 4
	s_add_i32 s19, s17, 4
	s_add_i32 s20, s16, 8
	s_add_i32 s21, s17, 8
	s_add_i32 s22, s16, 12
	s_add_i32 s23, s17, 12
	s_add_i32 s24, s16, 16
	s_add_i32 s25, s17, 16
	s_add_i32 s26, s16, 20
	s_add_i32 s27, s17, 20
	s_add_i32 s28, s16, 24
	s_add_i32 s29, s17, 24
	s_add_i32 s30, s16, 28
	s_add_i32 s31, s17, 28
	v_mad_i64_i32 v[24:25], s[14:15], v23, s12, v[16:17]
	v_mad_i64_i32 v[26:27], s[14:15], v18, s12, v[16:17]
	v_or_b32_e32 v18, s18, v3
	v_or_b32_e32 v23, s19, v4
	v_or_b32_e32 v34, s20, v3
	v_or_b32_e32 v32, s21, v4
	v_or_b32_e32 v38, s22, v3
	v_or_b32_e32 v36, s23, v4
	v_or_b32_e32 v42, s24, v3
	v_or_b32_e32 v40, s25, v4
	v_or_b32_e32 v46, s26, v3
	v_or_b32_e32 v44, s27, v4
	v_or_b32_e32 v50, s28, v3
	v_or_b32_e32 v48, s29, v4
	v_or_b32_e32 v54, s30, v3
	v_or_b32_e32 v52, s31, v4
	v_mad_i64_i32 v[28:29], s[14:15], v23, s12, v[16:17]
	v_mad_i64_i32 v[30:31], s[14:15], v18, s12, v[16:17]
	v_mad_i64_i32 v[32:33], s[14:15], v32, s12, v[16:17]
	v_mad_i64_i32 v[34:35], s[14:15], v34, s12, v[16:17]
	v_mad_i64_i32 v[36:37], s[14:15], v36, s12, v[16:17]
	v_mad_i64_i32 v[38:39], s[14:15], v38, s12, v[16:17]
	v_mad_i64_i32 v[40:41], s[14:15], v40, s12, v[16:17]
	v_mad_i64_i32 v[42:43], s[14:15], v42, s12, v[16:17]
	v_mad_i64_i32 v[44:45], s[14:15], v44, s12, v[16:17]
	v_mad_i64_i32 v[46:47], s[14:15], v46, s12, v[16:17]
	v_mad_i64_i32 v[48:49], s[14:15], v48, s12, v[16:17]
	v_mad_i64_i32 v[50:51], s[14:15], v50, s12, v[16:17]
	v_mad_i64_i32 v[52:53], s[14:15], v52, s12, v[16:17]
	v_mad_i64_i32 v[54:55], s[14:15], v54, s12, v[16:17]
	global_load_dword v18, v[24:25], off nt
	global_load_dword v23, v[26:27], off nt
	global_load_dword v56, v[28:29], off nt
	global_load_dword v57, v[30:31], off nt
	global_load_dword v58, v[32:33], off nt
	global_load_dword v59, v[34:35], off nt
	global_load_dword v60, v[36:37], off nt
	global_load_dword v61, v[38:39], off nt
	global_load_dword v62, v[40:41], off nt
	global_load_dword v63, v[42:43], off nt
	global_load_dword v64, v[44:45], off nt
	global_load_dword v65, v[46:47], off nt
	global_load_dword v66, v[48:49], off nt
	global_load_dword v67, v[50:51], off nt
	global_load_dword v68, v[52:53], off nt
	global_load_dword v69, v[54:55], off nt
	v_or_b32_e32 v26, s16, v1
	v_or_b32_e32 v24, s17, v2
	s_add_i32 s5, s5, 16
	s_add_i32 s2, s2, 16
	s_add_i32 s7, s7, -16
	v_mad_u64_u32 v[24:25], s[14:15], v24, s8, v[8:9]
	v_mad_u64_u32 v[26:27], s[14:15], v26, s8, v[8:9]
	v_or_b32_e32 v25, s18, v1
	v_or_b32_e32 v27, s19, v2
	v_or_b32_e32 v34, s20, v1
	v_or_b32_e32 v32, s21, v2
	v_or_b32_e32 v38, s22, v1
	v_or_b32_e32 v36, s23, v2
	v_or_b32_e32 v42, s24, v1
	v_or_b32_e32 v40, s25, v2
	v_or_b32_e32 v46, s26, v1
	v_or_b32_e32 v44, s27, v2
	v_or_b32_e32 v50, s28, v1
	v_or_b32_e32 v48, s29, v2
	v_or_b32_e32 v54, s30, v1
	v_or_b32_e32 v52, s31, v2
	s_cmp_lg_u32 s7, 0
	v_mad_u64_u32 v[28:29], s[14:15], v27, s8, v[8:9]
	v_mad_u64_u32 v[30:31], s[14:15], v25, s8, v[8:9]
	v_mad_u64_u32 v[32:33], s[14:15], v32, s8, v[8:9]
	v_mad_u64_u32 v[34:35], s[14:15], v34, s8, v[8:9]
	v_mad_u64_u32 v[36:37], s[14:15], v36, s8, v[8:9]
	v_mad_u64_u32 v[38:39], s[14:15], v38, s8, v[8:9]
	v_mad_u64_u32 v[40:41], s[14:15], v40, s8, v[8:9]
	v_mad_u64_u32 v[42:43], s[14:15], v42, s8, v[8:9]
	v_mad_u64_u32 v[44:45], s[14:15], v44, s8, v[8:9]
	v_mad_u64_u32 v[46:47], s[14:15], v46, s8, v[8:9]
	v_mad_u64_u32 v[48:49], s[14:15], v48, s8, v[8:9]
	v_mad_u64_u32 v[50:51], s[14:15], v50, s8, v[8:9]
	v_mad_u64_u32 v[52:53], s[14:15], v52, s8, v[8:9]
	v_mad_u64_u32 v[54:55], s[14:15], v54, s8, v[8:9]
	s_waitcnt vmcnt(15)
	ds_write_b32 v24, v18
	s_waitcnt vmcnt(14)
	ds_write_b32 v26, v23
	s_waitcnt vmcnt(13)
	ds_write_b32 v28, v56
	s_waitcnt vmcnt(12)
	ds_write_b32 v30, v57
	s_waitcnt vmcnt(11)
	ds_write_b32 v32, v58
	s_waitcnt vmcnt(10)
	ds_write_b32 v34, v59
	s_waitcnt vmcnt(9)
	ds_write_b32 v36, v60
	s_waitcnt vmcnt(8)
	ds_write_b32 v38, v61
	s_waitcnt vmcnt(7)
	ds_write_b32 v40, v62
	s_waitcnt vmcnt(6)
	ds_write_b32 v42, v63
	s_waitcnt vmcnt(5)
	ds_write_b32 v44, v64
	s_waitcnt vmcnt(4)
	ds_write_b32 v46, v65
	s_waitcnt vmcnt(3)
	ds_write_b32 v48, v66
	s_waitcnt vmcnt(2)
	ds_write_b32 v50, v67
	s_waitcnt vmcnt(1)
	ds_write_b32 v52, v68
	s_waitcnt vmcnt(0)
	ds_write_b32 v54, v69
	s_cbranch_scc1 .LBB0_21
	s_waitcnt lgkmcnt(0)
	ds_read2_b32 v[16:17], v19 offset1:8
	ds_read2_b32 v[30:31], v19 offset0:33 offset1:41
	ds_read2_b32 v[32:33], v19 offset0:66 offset1:74
	ds_read2_b32 v[34:35], v19 offset0:99 offset1:107
	ds_read2_b32 v[36:37], v19 offset0:132 offset1:140
	ds_read2_b32 v[38:39], v19 offset0:165 offset1:173
	s_waitcnt lgkmcnt(5)
	v_bfe_u32 v3, v16, 16, 1
	v_add3_u32 v3, v16, v3, s9
	s_waitcnt lgkmcnt(4)
	v_bfe_u32 v4, v30, 16, 1
	v_lshrrev_b32_e32 v3, 16, v3
	v_add3_u32 v4, v30, v4, s9
	v_and_or_b32 v24, v4, s11, v3
	s_waitcnt lgkmcnt(3)
	v_bfe_u32 v3, v32, 16, 1
	v_add3_u32 v3, v32, v3, s9
	s_waitcnt lgkmcnt(2)
	v_bfe_u32 v4, v34, 16, 1
	ds_read2_b32 v[40:41], v19 offset0:198 offset1:206
	v_lshrrev_b32_e32 v3, 16, v3
	v_add3_u32 v4, v34, v4, s9
	ds_read2_b32 v[42:43], v19 offset0:231 offset1:239
	v_and_or_b32 v25, v4, s11, v3
	s_waitcnt lgkmcnt(3)
	v_bfe_u32 v3, v36, 16, 1
	v_add3_u32 v3, v36, v3, s9
	s_waitcnt lgkmcnt(2)
	v_bfe_u32 v4, v38, 16, 1
	v_lshrrev_b32_e32 v3, 16, v3
	v_add3_u32 v4, v38, v4, s9
	v_and_or_b32 v26, v4, s11, v3
	s_waitcnt lgkmcnt(1)
	v_bfe_u32 v3, v40, 16, 1
	v_add3_u32 v3, v40, v3, s9
	s_waitcnt lgkmcnt(0)
	v_bfe_u32 v4, v42, 16, 1
	v_lshrrev_b32_e32 v3, 16, v3
	v_add3_u32 v4, v42, v4, s9
	v_or_b32_e32 v44, s4, v9
	s_ashr_i32 s7, s6, 31
	v_and_or_b32 v27, v4, s11, v3
	v_ashrrev_i32_e32 v45, 31, v44
	v_bfe_u32 v3, v17, 16, 1
	v_lshl_add_u64 v[28:29], s[6:7], 1, v[14:15]
	v_lshlrev_b64 v[44:45], 11, v[44:45]
	v_add3_u32 v3, v17, v3, s9
	v_bfe_u32 v4, v31, 16, 1
	v_lshl_add_u64 v[44:45], v[28:29], 0, v[44:45]
	v_lshrrev_b32_e32 v3, 16, v3
	v_add3_u32 v4, v31, v4, s9
	global_store_dwordx4 v[44:45], v[24:27], off
	v_or_b32_e32 v16, s4, v20
	v_ashrrev_i32_e32 v17, 31, v16
	v_and_or_b32 v24, v4, s11, v3
	v_bfe_u32 v3, v33, 16, 1
	v_add3_u32 v3, v33, v3, s9
	v_bfe_u32 v4, v35, 16, 1
	v_lshrrev_b32_e32 v3, 16, v3
	v_add3_u32 v4, v35, v4, s9
	v_and_or_b32 v25, v4, s11, v3
	v_bfe_u32 v3, v37, 16, 1
	v_add3_u32 v3, v37, v3, s9
	v_bfe_u32 v4, v39, 16, 1
	v_lshrrev_b32_e32 v3, 16, v3
	v_add3_u32 v4, v39, v4, s9
	v_and_or_b32 v26, v4, s11, v3
	v_bfe_u32 v3, v41, 16, 1
	v_add3_u32 v3, v41, v3, s9
	v_bfe_u32 v4, v43, 16, 1
	v_lshrrev_b32_e32 v3, 16, v3
	v_add3_u32 v4, v43, v4, s9
	v_lshlrev_b64 v[16:17], 11, v[16:17]
	v_and_or_b32 v27, v4, s11, v3
	ds_read2_b32 v[30:31], v19 offset0:16 offset1:24
	v_lshl_add_u64 v[16:17], v[28:29], 0, v[16:17]
	global_store_dwordx4 v[16:17], v[24:27], off
	ds_read2_b32 v[16:17], v19 offset0:49 offset1:57
	ds_read2_b32 v[32:33], v19 offset0:82 offset1:90
	ds_read2_b32 v[34:35], v19 offset0:115 offset1:123
	s_waitcnt lgkmcnt(3)
	v_bfe_u32 v3, v30, 16, 1
	v_add3_u32 v3, v30, v3, s9
	s_waitcnt lgkmcnt(2)
	v_bfe_u32 v4, v16, 16, 1
	ds_read2_b32 v[36:37], v19 offset0:148 offset1:156
	v_lshrrev_b32_e32 v3, 16, v3
	v_add3_u32 v4, v16, v4, s9
	ds_read2_b32 v[38:39], v19 offset0:181 offset1:189
	v_and_or_b32 v24, v4, s11, v3
	s_waitcnt lgkmcnt(3)
	v_bfe_u32 v3, v32, 16, 1
	v_add3_u32 v3, v32, v3, s9
	s_waitcnt lgkmcnt(2)
	v_bfe_u32 v4, v34, 16, 1
	ds_read2_b32 v[40:41], v19 offset0:214 offset1:222
	v_lshrrev_b32_e32 v3, 16, v3
	v_add3_u32 v4, v34, v4, s9
	ds_read2_b32 v[42:43], v19 offset0:247 offset1:255
	v_and_or_b32 v25, v4, s11, v3
	s_waitcnt lgkmcnt(3)
	v_bfe_u32 v3, v36, 16, 1
	v_add3_u32 v3, v36, v3, s9
	s_waitcnt lgkmcnt(2)
	v_bfe_u32 v4, v38, 16, 1
	v_lshrrev_b32_e32 v3, 16, v3
	v_add3_u32 v4, v38, v4, s9
	v_and_or_b32 v26, v4, s11, v3
	s_waitcnt lgkmcnt(1)
	v_bfe_u32 v3, v40, 16, 1
	v_add3_u32 v3, v40, v3, s9
	s_waitcnt lgkmcnt(0)
	v_bfe_u32 v4, v42, 16, 1
	v_lshrrev_b32_e32 v3, 16, v3
	v_add3_u32 v4, v42, v4, s9
	v_or_b32_e32 v44, s4, v21
	v_and_or_b32 v27, v4, s11, v3
	v_ashrrev_i32_e32 v45, 31, v44
	v_bfe_u32 v3, v31, 16, 1
	v_lshlrev_b64 v[44:45], 11, v[44:45]
	v_add3_u32 v3, v31, v3, s9
	v_bfe_u32 v4, v17, 16, 1
	v_lshl_add_u64 v[44:45], v[28:29], 0, v[44:45]
	v_lshrrev_b32_e32 v3, 16, v3
	v_add3_u32 v4, v17, v4, s9
	global_store_dwordx4 v[44:45], v[24:27], off
	v_or_b32_e32 v16, s4, v22
	v_ashrrev_i32_e32 v17, 31, v16
	v_and_or_b32 v24, v4, s11, v3
	v_bfe_u32 v3, v33, 16, 1
	v_add3_u32 v3, v33, v3, s9
	v_bfe_u32 v4, v35, 16, 1
	v_lshrrev_b32_e32 v3, 16, v3
	v_add3_u32 v4, v35, v4, s9
	v_and_or_b32 v25, v4, s11, v3
	v_bfe_u32 v3, v37, 16, 1
	v_add3_u32 v3, v37, v3, s9
	v_bfe_u32 v4, v39, 16, 1
	v_lshrrev_b32_e32 v3, 16, v3
	v_add3_u32 v4, v39, v4, s9
	v_and_or_b32 v26, v4, s11, v3
	v_bfe_u32 v3, v41, 16, 1
	v_add3_u32 v3, v41, v3, s9
	v_bfe_u32 v4, v43, 16, 1
	v_lshrrev_b32_e32 v3, 16, v3
	v_add3_u32 v4, v43, v4, s9
	v_lshlrev_b64 v[16:17], 11, v[16:17]
	v_and_or_b32 v27, v4, s11, v3
	v_lshl_add_u64 v[16:17], v[28:29], 0, v[16:17]
	global_store_dwordx4 v[16:17], v[24:27], off
	s_waitcnt lgkmcnt(0)
	s_branch .LBB0_14

.LBB0_26:
	s_lshl_b32 s13, s12, 1
	s_lshl_b32 s14, s11, 1
	v_or_b32_e32 v4, s14, v2
	s_add_i32 s16, s13, 4
	s_add_i32 s17, s14, 4
	v_mov_b32_e32 v21, v5
	s_add_i32 s19, s14, 8
	s_add_i32 s21, s14, 12
	s_add_i32 s23, s14, 16
	s_add_i32 s25, s14, 20
	s_add_i32 s27, s14, 24
	s_add_i32 s28, s14, 28
	v_lshlrev_b64 v[36:37], 11, v[4:5]
	v_mad_u64_u32 v[38:39], s[14:15], v4, s4, v[6:7]
	v_or_b32_e32 v20, s16, v1
	v_or_b32_e32 v4, s17, v2
	v_mov_b32_e32 v19, v5
	v_or_b32_e32 v18, s13, v1
	v_lshlrev_b64 v[40:41], 11, v[20:21]
	v_lshlrev_b64 v[42:43], 11, v[4:5]
	v_mad_u64_u32 v[44:45], s[14:15], v4, s4, v[6:7]
	v_or_b32_e32 v4, s19, v2
	s_add_i32 s18, s13, 8
	s_add_i32 s20, s13, 12
	v_lshlrev_b64 v[34:35], 11, v[18:19]
	v_lshl_add_u64 v[36:37], v[12:13], 0, v[36:37]
	v_lshl_add_u64 v[40:41], v[12:13], 0, v[40:41]
	v_lshlrev_b64 v[58:59], 11, v[4:5]
	v_mad_u64_u32 v[60:61], s[14:15], v4, s4, v[6:7]
	v_or_b32_e32 v4, s21, v2
	v_mov_b32_e32 v23, v5
	v_mov_b32_e32 v25, v5
	s_add_i32 s22, s13, 16
	v_or_b32_e32 v22, s18, v1
	v_or_b32_e32 v24, s20, v1
	v_lshl_add_u64 v[34:35], v[12:13], 0, v[34:35]
	v_lshl_add_u64 v[42:43], v[12:13], 0, v[42:43]
	global_load_dword v17, v[36:37], off nt
	global_load_dword v39, v[34:35], off nt
	global_load_dword v45, v[42:43], off nt
	global_load_dword v61, v[40:41], off nt
	v_lshlrev_b64 v[36:37], 11, v[4:5]
	v_mad_u64_u32 v[40:41], s[14:15], v4, s4, v[6:7]
	v_or_b32_e32 v4, s23, v2
	v_mov_b32_e32 v27, v5
	s_add_i32 s24, s13, 20
	v_or_b32_e32 v26, s22, v1
	v_lshlrev_b64 v[46:47], 11, v[22:23]
	v_lshlrev_b64 v[48:49], 11, v[24:25]
	v_lshl_add_u64 v[34:35], v[12:13], 0, v[58:59]
	v_lshl_add_u64 v[36:37], v[12:13], 0, v[36:37]
	v_lshlrev_b64 v[42:43], 11, v[4:5]
	v_mad_u64_u32 v[58:59], s[14:15], v4, s4, v[6:7]
	v_or_b32_e32 v4, s25, v2
	v_mov_b32_e32 v29, v5
	v_or_b32_e32 v28, s24, v1
	v_lshlrev_b64 v[50:51], 11, v[26:27]
	v_lshl_add_u64 v[46:47], v[12:13], 0, v[46:47]
	v_lshl_add_u64 v[48:49], v[12:13], 0, v[48:49]
	global_load_dword v41, v[34:35], off nt
	global_load_dword v59, v[46:47], off nt
	global_load_dword v62, v[36:37], off nt
	global_load_dword v63, v[48:49], off nt
	v_lshl_add_u64 v[34:35], v[12:13], 0, v[42:43]
	v_lshlrev_b64 v[36:37], 11, v[4:5]
	v_mad_u64_u32 v[42:43], s[14:15], v4, s4, v[6:7]
	v_or_b32_e32 v4, s27, v2
	s_add_i32 s26, s13, 24
	s_add_i32 s13, s13, 28
	v_lshlrev_b64 v[52:53], 11, v[28:29]
	v_lshl_add_u64 v[50:51], v[12:13], 0, v[50:51]
	v_lshl_add_u64 v[36:37], v[12:13], 0, v[36:37]
	v_lshlrev_b64 v[46:47], 11, v[4:5]
	v_mad_u64_u32 v[48:49], s[14:15], v4, s4, v[6:7]
	v_or_b32_e32 v4, s28, v2
	v_mov_b32_e32 v31, v5
	v_mov_b32_e32 v33, v5
	v_or_b32_e32 v30, s26, v1
	v_or_b32_e32 v32, s13, v1
	v_lshl_add_u64 v[52:53], v[12:13], 0, v[52:53]
	global_load_dword v43, v[34:35], off nt
	global_load_dword v49, v[50:51], off nt
	s_nop 0
	global_load_dword v50, v[36:37], off nt
	global_load_dword v51, v[52:53], off nt
	v_lshlrev_b64 v[36:37], 11, v[4:5]
	v_lshlrev_b64 v[54:55], 11, v[30:31]
	v_lshlrev_b64 v[56:57], 11, v[32:33]
	v_lshl_add_u64 v[34:35], v[12:13], 0, v[46:47]
	v_lshl_add_u64 v[36:37], v[12:13], 0, v[36:37]
	v_lshl_add_u64 v[54:55], v[12:13], 0, v[54:55]
	v_lshl_add_u64 v[56:57], v[12:13], 0, v[56:57]
	global_load_dword v46, v[34:35], off nt
	global_load_dword v47, v[54:55], off nt
	s_nop 0
	global_load_dword v36, v[36:37], off nt
	s_nop 0
	global_load_dword v37, v[56:57], off nt
	s_add_i32 s11, s11, 16
	s_add_i32 s12, s12, 16
	s_add_i32 s9, s9, -16
	s_cmp_lg_u32 s9, 0
	v_mad_u64_u32 v[18:19], s[14:15], v18, s4, v[6:7]
	v_mad_u64_u32 v[20:21], s[14:15], v20, s4, v[6:7]
	v_mad_u64_u32 v[22:23], s[14:15], v22, s4, v[6:7]
	v_mad_u64_u32 v[24:25], s[14:15], v24, s4, v[6:7]
	v_mad_u64_u32 v[26:27], s[14:15], v26, s4, v[6:7]
	v_mad_u64_u32 v[28:29], s[14:15], v28, s4, v[6:7]
	v_mad_u64_u32 v[30:31], s[14:15], v30, s4, v[6:7]
	v_mad_u64_u32 v[32:33], s[14:15], v32, s4, v[6:7]
	v_mad_u64_u32 v[34:35], s[14:15], v4, s4, v[6:7]
	s_waitcnt vmcnt(15)
	ds_write_b32 v38, v17
	s_waitcnt vmcnt(14)
	ds_write_b32 v18, v39
	s_waitcnt vmcnt(13)
	ds_write_b32 v44, v45
	s_waitcnt vmcnt(12)
	ds_write_b32 v20, v61
	s_waitcnt vmcnt(11)
	ds_write_b32 v60, v41
	s_waitcnt vmcnt(10)
	ds_write_b32 v22, v59
	s_waitcnt vmcnt(9)
	ds_write_b32 v40, v62
	s_waitcnt vmcnt(8)
	ds_write_b32 v24, v63
	s_waitcnt vmcnt(7)
	ds_write_b32 v58, v43
	s_waitcnt vmcnt(6)
	ds_write_b32 v26, v49
	s_waitcnt vmcnt(5)
	ds_write_b32 v42, v50
	s_waitcnt vmcnt(4)
	ds_write_b32 v28, v51
	s_waitcnt vmcnt(3)
	ds_write_b32 v48, v46
	s_waitcnt vmcnt(2)
	ds_write_b32 v30, v47
	s_waitcnt vmcnt(1)
	ds_write_b32 v34, v36
	s_waitcnt vmcnt(0)
	ds_write_b32 v32, v37
	s_cbranch_scc1 .LBB0_26
	s_waitcnt lgkmcnt(0)
	ds_read2_b32 v[12:13], v7 offset1:8
	ds_read2_b32 v[24:25], v7 offset0:33 offset1:41
	ds_read2_b32 v[26:27], v7 offset0:66 offset1:74
	ds_read2_b32 v[28:29], v7 offset0:99 offset1:107
	ds_read2_b32 v[30:31], v7 offset0:132 offset1:140
	s_waitcnt lgkmcnt(4)
	v_bfe_u32 v4, v12, 16, 1
	v_add3_u32 v4, v12, v4, s1
	s_waitcnt lgkmcnt(3)
	v_bfe_u32 v12, v24, 16, 1
	v_lshrrev_b32_e32 v4, 16, v4
	v_add3_u32 v12, v24, v12, s1
	ds_read2_b32 v[32:33], v7 offset0:165 offset1:173
	v_and_or_b32 v18, v12, s5, v4
	s_waitcnt lgkmcnt(3)
	v_bfe_u32 v4, v26, 16, 1
	v_add3_u32 v4, v26, v4, s1
	s_waitcnt lgkmcnt(2)
	v_bfe_u32 v12, v28, 16, 1
	ds_read2_b32 v[34:35], v7 offset0:198 offset1:206
	v_lshrrev_b32_e32 v4, 16, v4
	v_add3_u32 v12, v28, v12, s1
	ds_read2_b32 v[36:37], v7 offset0:231 offset1:239
	v_and_or_b32 v19, v12, s5, v4
	s_waitcnt lgkmcnt(3)
	v_bfe_u32 v4, v30, 16, 1
	v_add3_u32 v4, v30, v4, s1
	s_waitcnt lgkmcnt(2)
	v_bfe_u32 v12, v32, 16, 1
	s_lshl_b32 s8, s8, 16
	v_lshrrev_b32_e32 v4, 16, v4
	v_add3_u32 v12, v32, v12, s1
	s_and_b64 s[2:3], s[2:3], exec
	v_and_or_b32 v20, v12, s5, v4
	s_waitcnt lgkmcnt(1)
	v_bfe_u32 v4, v34, 16, 1
	s_cselect_b32 s2, s44, s46
	v_add3_u32 v4, v34, v4, s1
	s_waitcnt lgkmcnt(0)
	v_bfe_u32 v12, v36, 16, 1
	s_cselect_b32 s3, s45, s47
	s_add_u32 s2, s2, s8
	v_lshrrev_b32_e32 v4, 16, v4
	v_add3_u32 v12, v36, v12, s1
	s_addc_u32 s3, s3, 0
	v_and_or_b32 v21, v12, s5, v4
	v_or_b32_e32 v4, s7, v3
	v_lshl_add_u64 v[22:23], s[2:3], 0, v[10:11]
	v_lshlrev_b32_e32 v4, 7, v4
	v_lshl_add_u64 v[38:39], v[22:23], 0, v[4:5]
	v_bfe_u32 v4, v13, 16, 1
	v_add3_u32 v4, v13, v4, s1
	v_bfe_u32 v12, v25, 16, 1
	v_lshrrev_b32_e32 v4, 16, v4
	v_add3_u32 v12, v25, v12, s1
	global_store_dwordx4 v[38:39], v[18:21], off
	s_add_i32 s6, s6, s10
	s_cmp_gt_i32 s6, 63
	v_and_or_b32 v18, v12, s5, v4
	v_bfe_u32 v4, v27, 16, 1
	v_add3_u32 v4, v27, v4, s1
	v_bfe_u32 v12, v29, 16, 1
	v_lshrrev_b32_e32 v4, 16, v4
	v_add3_u32 v12, v29, v12, s1
	v_and_or_b32 v19, v12, s5, v4
	v_bfe_u32 v4, v31, 16, 1
	v_add3_u32 v4, v31, v4, s1
	v_bfe_u32 v12, v33, 16, 1
	v_lshrrev_b32_e32 v4, 16, v4
	v_add3_u32 v12, v33, v12, s1
	v_and_or_b32 v20, v12, s5, v4
	v_bfe_u32 v4, v35, 16, 1
	v_add3_u32 v4, v35, v4, s1
	v_bfe_u32 v12, v37, 16, 1
	v_lshrrev_b32_e32 v4, 16, v4
	v_add3_u32 v12, v37, v12, s1
	v_and_or_b32 v21, v12, s5, v4
	v_or_b32_e32 v4, s7, v14
	v_lshlrev_b32_e32 v4, 7, v4
	ds_read2_b32 v[12:13], v7 offset0:16 offset1:24
	v_lshl_add_u64 v[24:25], v[22:23], 0, v[4:5]
	global_store_dwordx4 v[24:25], v[18:21], off
	ds_read2_b32 v[24:25], v7 offset0:49 offset1:57
	ds_read2_b32 v[26:27], v7 offset0:82 offset1:90
	ds_read2_b32 v[28:29], v7 offset0:115 offset1:123
	s_waitcnt lgkmcnt(3)
	v_bfe_u32 v4, v12, 16, 1
	v_add3_u32 v4, v12, v4, s1
	s_waitcnt lgkmcnt(2)
	v_bfe_u32 v12, v24, 16, 1
	ds_read2_b32 v[30:31], v7 offset0:148 offset1:156
	v_lshrrev_b32_e32 v4, 16, v4
	v_add3_u32 v12, v24, v12, s1
	ds_read2_b32 v[32:33], v7 offset0:181 offset1:189
	v_and_or_b32 v18, v12, s5, v4
	s_waitcnt lgkmcnt(3)
	v_bfe_u32 v4, v26, 16, 1
	v_add3_u32 v4, v26, v4, s1
	s_waitcnt lgkmcnt(2)
	v_bfe_u32 v12, v28, 16, 1
	ds_read2_b32 v[34:35], v7 offset0:214 offset1:222
	v_lshrrev_b32_e32 v4, 16, v4
	v_add3_u32 v12, v28, v12, s1
	ds_read2_b32 v[36:37], v7 offset0:247 offset1:255
	v_and_or_b32 v19, v12, s5, v4
	s_waitcnt lgkmcnt(3)
	v_bfe_u32 v4, v30, 16, 1
	v_add3_u32 v4, v30, v4, s1
	s_waitcnt lgkmcnt(2)
	v_bfe_u32 v12, v32, 16, 1
	v_lshrrev_b32_e32 v4, 16, v4
	v_add3_u32 v12, v32, v12, s1
	v_and_or_b32 v20, v12, s5, v4
	s_waitcnt lgkmcnt(1)
	v_bfe_u32 v4, v34, 16, 1
	v_add3_u32 v4, v34, v4, s1
	s_waitcnt lgkmcnt(0)
	v_bfe_u32 v12, v36, 16, 1
	v_lshrrev_b32_e32 v4, 16, v4
	v_add3_u32 v12, v36, v12, s1
	v_and_or_b32 v21, v12, s5, v4
	v_or_b32_e32 v4, s7, v15
	v_lshlrev_b32_e32 v4, 7, v4
	v_lshl_add_u64 v[38:39], v[22:23], 0, v[4:5]
	v_bfe_u32 v4, v13, 16, 1
	v_add3_u32 v4, v13, v4, s1
	v_bfe_u32 v12, v25, 16, 1
	v_lshrrev_b32_e32 v4, 16, v4
	v_add3_u32 v12, v25, v12, s1
	global_store_dwordx4 v[38:39], v[18:21], off
	s_nop 1
	v_and_or_b32 v18, v12, s5, v4
	v_bfe_u32 v4, v27, 16, 1
	v_add3_u32 v4, v27, v4, s1
	v_bfe_u32 v12, v29, 16, 1
	v_lshrrev_b32_e32 v4, 16, v4
	v_add3_u32 v12, v29, v12, s1
	v_and_or_b32 v19, v12, s5, v4
	v_bfe_u32 v4, v31, 16, 1
	v_add3_u32 v4, v31, v4, s1
	v_bfe_u32 v12, v33, 16, 1
	v_lshrrev_b32_e32 v4, 16, v4
	v_add3_u32 v12, v33, v12, s1
	v_and_or_b32 v20, v12, s5, v4
	v_bfe_u32 v4, v35, 16, 1
	v_add3_u32 v4, v35, v4, s1
	v_bfe_u32 v12, v37, 16, 1
	v_lshrrev_b32_e32 v4, 16, v4
	v_add3_u32 v12, v37, v12, s1
	v_and_or_b32 v21, v12, s5, v4
	v_or_b32_e32 v4, s7, v16
	v_lshlrev_b32_e32 v4, 7, v4
	v_lshl_add_u64 v[12:13], v[22:23], 0, v[4:5]
	global_store_dwordx4 v[12:13], v[18:21], off
	s_waitcnt lgkmcnt(0)
	s_cbranch_scc0 .LBB0_25

.LBB0_31:
	global_load_dwordx4 v[20:23], v[10:11], off offset:-3072 nt
	global_load_dwordx4 v[24:27], v[10:11], off offset:-2048 nt
	global_load_dwordx4 v[28:31], v[10:11], off offset:-1024 nt
	global_load_dwordx4 v[32:35], v[10:11], off nt
	s_waitcnt vmcnt(3)
	v_mul_f32_e32 v19, v21, v21
	v_mul_f32_e32 v36, v23, v23
	s_waitcnt vmcnt(2)
	v_mul_f32_e32 v37, v25, v25
	v_mul_f32_e32 v38, v27, v27
	s_waitcnt vmcnt(1)
	v_mul_f32_e32 v39, v29, v29
	v_mul_f32_e32 v40, v31, v31
	v_fmac_f32_e32 v19, v20, v20
	v_fmac_f32_e32 v36, v22, v22
	v_fmac_f32_e32 v37, v24, v24
	v_fmac_f32_e32 v38, v26, v26
	s_waitcnt vmcnt(0)
	v_mul_f32_e32 v41, v33, v33
	v_mul_f32_e32 v42, v35, v35
	v_fmac_f32_e32 v39, v28, v28
	v_fmac_f32_e32 v40, v30, v30
	v_add_f32_e32 v19, v19, v36
	v_add_f32_e32 v36, v37, v38
	v_fmac_f32_e32 v41, v32, v32
	v_fmac_f32_e32 v42, v34, v34
	v_add_f32_e32 v37, v39, v40
	v_add_f32_e32 v19, v19, v36
	v_add_f32_e32 v38, v41, v42
	v_add_f32_e32 v19, v19, v37
	v_add_f32_e32 v19, v19, v38
	ds_bpermute_b32 v36, v1, v19
	s_waitcnt lgkmcnt(0)
	v_add_f32_e32 v19, v19, v36
	ds_bpermute_b32 v44, v12, v19
	global_load_dwordx4 v[36:39], v[2:3], off
	global_load_dwordx4 v[40:43], v[2:3], off offset:1024
	s_waitcnt lgkmcnt(0)
	v_add_f32_e32 v19, v19, v44
	ds_bpermute_b32 v48, v13, v19
	global_load_dwordx4 v[44:47], v[2:3], off offset:2048
	s_waitcnt lgkmcnt(0)
	v_add_f32_e32 v19, v19, v48
	global_load_dwordx4 v[48:51], v[2:3], off offset:3072
	ds_bpermute_b32 v52, v14, v19
	s_waitcnt lgkmcnt(0)
	v_add_f32_e32 v19, v19, v52
	ds_bpermute_b32 v52, v15, v19
	s_waitcnt lgkmcnt(0)
	v_add_f32_e32 v19, v19, v52
	ds_bpermute_b32 v52, v16, v19
	s_waitcnt lgkmcnt(0)
	v_add_f32_e32 v19, v19, v52
	v_fmamk_f32 v19, v19, 0x3a800000, v17
	v_mul_f32_e32 v52, 0x4f800000, v19
	v_cmp_gt_f32_e32 vcc, s1, v19
	s_nop 1
	v_cndmask_b32_e32 v19, v19, v52, vcc
	v_sqrt_f32_e32 v52, v19
	s_nop 0
	v_add_u32_e32 v53, -1, v52
	v_add_u32_e32 v54, 1, v52
	v_fma_f32 v55, -v53, v52, v19
	v_fma_f32 v56, -v54, v52, v19
	v_cmp_ge_f32_e64 s[4:5], 0, v55
	s_nop 1
	v_cndmask_b32_e64 v52, v52, v53, s[4:5]
	v_cmp_lt_f32_e64 s[4:5], 0, v56
	s_nop 1
	v_cndmask_b32_e64 v52, v52, v54, s[4:5]
	v_mul_f32_e32 v53, 0x37800000, v52
	v_cndmask_b32_e32 v52, v52, v53, vcc
	v_cmp_class_f32_e32 vcc, v19, v18
	s_nop 1
	v_cndmask_b32_e32 v19, v52, v19, vcc
	v_div_scale_f32 v52, s[4:5], v19, v19, 1.0
	v_rcp_f32_e32 v53, v52
	v_div_scale_f32 v54, vcc, 1.0, v19, 1.0
	s_add_i32 s4, s10, s0
	v_fma_f32 v55, -v52, v53, 1.0
	v_fmac_f32_e32 v53, v55, v53
	v_mul_f32_e32 v55, v54, v53
	v_fma_f32 v56, -v52, v55, v54
	v_fmac_f32_e32 v55, v56, v53
	v_fma_f32 v52, -v52, v55, v54
	v_div_fmas_f32 v52, v52, v53, v55
	v_div_fixup_f32 v19, v52, v19, 1.0
	v_mul_f32_e32 v20, v20, v19
	v_mul_f32_e32 v22, v22, v19
	v_mul_f32_e32 v26, v26, v19
	v_mul_f32_e32 v32, v32, v19
	v_mul_f32_e32 v34, v34, v19
	v_mul_f32_e32 v21, v21, v19
	v_mul_f32_e32 v23, v23, v19
	v_mul_f32_e32 v24, v24, v19
	v_mul_f32_e32 v25, v25, v19
	v_mul_f32_e32 v27, v27, v19
	v_mul_f32_e32 v28, v28, v19
	v_mul_f32_e32 v29, v29, v19
	v_mul_f32_e32 v30, v30, v19
	v_mul_f32_e32 v31, v31, v19
	v_mul_f32_e32 v33, v33, v19
	v_mul_f32_e32 v19, v35, v19
	s_waitcnt vmcnt(3)
	v_mul_f32_e32 v20, v36, v20
	v_mul_f32_e32 v22, v38, v22
	s_waitcnt vmcnt(2)
	v_mul_f32_e32 v26, v42, v26
	s_waitcnt vmcnt(0)
	v_mul_f32_e32 v32, v32, v48
	v_mul_f32_e32 v34, v34, v50
	v_mul_f32_e32 v21, v37, v21
	v_mul_f32_e32 v23, v39, v23
	v_mul_f32_e32 v24, v40, v24
	v_mul_f32_e32 v25, v41, v25
	v_mul_f32_e32 v27, v43, v27
	v_mul_f32_e32 v28, v44, v28
	v_mul_f32_e32 v30, v46, v30
	v_mul_f32_e32 v31, v47, v31
	v_mul_f32_e32 v33, v33, v49
	v_mul_f32_e32 v19, v19, v51
	v_bfe_u32 v35, v20, 16, 1
	v_bfe_u32 v37, v22, 16, 1
	v_bfe_u32 v41, v26, 16, 1
	v_bfe_u32 v47, v32, 16, 1
	v_bfe_u32 v49, v34, 16, 1
	v_mul_f32_e32 v29, v45, v29
	v_bfe_u32 v36, v21, 16, 1
	v_bfe_u32 v38, v23, 16, 1
	v_bfe_u32 v39, v24, 16, 1
	v_bfe_u32 v42, v27, 16, 1
	v_bfe_u32 v43, v28, 16, 1
	v_bfe_u32 v45, v30, 16, 1
	v_bfe_u32 v48, v33, 16, 1
	v_bfe_u32 v50, v19, 16, 1
	v_add3_u32 v20, v20, v35, s3
	v_add3_u32 v22, v22, v37, s3
	v_add3_u32 v26, v26, v41, s3
	v_add3_u32 v32, v32, v47, s3
	v_add3_u32 v34, v34, v49, s3
	v_bfe_u32 v40, v25, 16, 1
	v_bfe_u32 v44, v29, 16, 1
	v_bfe_u32 v46, v31, 16, 1
	v_add3_u32 v21, v21, v36, s3
	v_add3_u32 v23, v23, v38, s3
	v_add3_u32 v24, v24, v39, s3
	v_add3_u32 v27, v27, v42, s3
	v_add3_u32 v28, v28, v43, s3
	v_add3_u32 v30, v30, v45, s3
	v_add3_u32 v33, v33, v48, s3
	v_add3_u32 v19, v19, v50, s3
	v_lshrrev_b32_e32 v20, 16, v20
	v_lshrrev_b32_e32 v22, 16, v22
	v_lshrrev_b32_e32 v26, 16, v26
	v_lshrrev_b32_e32 v32, 16, v32
	v_lshrrev_b32_e32 v34, 16, v34
	v_add3_u32 v25, v25, v40, s3
	v_add3_u32 v29, v29, v44, s3
	v_add3_u32 v31, v31, v46, s3
	v_lshrrev_b32_e32 v24, 16, v24
	v_lshrrev_b32_e32 v28, 16, v28
	v_lshrrev_b32_e32 v30, 16, v30
	v_and_or_b32 v20, v21, s13, v20
	v_and_or_b32 v21, v23, s13, v22
	v_and_or_b32 v23, v27, s13, v26
	v_and_or_b32 v26, v33, s13, v32
	v_and_or_b32 v27, v19, s13, v34
	s_cmpk_lt_i32 s4, 0x4000
	v_and_or_b32 v22, v25, s13, v24
	v_and_or_b32 v24, v29, s13, v28
	v_and_or_b32 v25, v31, s13, v30
	global_store_dwordx2 v[8:9], v[20:21], off
	global_store_dwordx2 v[8:9], v[22:23], off offset:512
	global_store_dwordx2 v[8:9], v[24:25], off offset:1024
	global_store_dwordx2 v[8:9], v[26:27], off offset:1536
	s_cbranch_scc0 .LBB0_34
	s_ashr_i32 s5, s4, 31
	s_lshl_b64 s[14:15], s[4:5], 12
	v_lshl_add_u64 v[32:33], v[4:5], 0, s[14:15]
	global_load_dwordx4 v[20:23], v[32:33], off nt
	global_load_dwordx4 v[24:27], v[32:33], off offset:1024 nt
	global_load_dwordx4 v[28:31], v[32:33], off offset:2048 nt
	s_nop 0
	global_load_dwordx4 v[32:35], v[32:33], off offset:3072 nt
	s_lshl_b64 s[14:15], s[4:5], 11
	s_waitcnt vmcnt(3)
	v_mul_f32_e32 v19, v21, v21
	v_mul_f32_e32 v36, v23, v23
	s_waitcnt vmcnt(2)
	v_mul_f32_e32 v37, v25, v25
	v_mul_f32_e32 v38, v27, v27
	s_waitcnt vmcnt(1)
	v_mul_f32_e32 v39, v29, v29
	v_mul_f32_e32 v40, v31, v31
	v_fmac_f32_e32 v19, v20, v20
	v_fmac_f32_e32 v36, v22, v22
	v_fmac_f32_e32 v37, v24, v24
	v_fmac_f32_e32 v38, v26, v26
	s_waitcnt vmcnt(0)
	v_mul_f32_e32 v41, v33, v33
	v_mul_f32_e32 v42, v35, v35
	v_fmac_f32_e32 v39, v28, v28
	v_fmac_f32_e32 v40, v30, v30
	v_add_f32_e32 v19, v19, v36
	v_add_f32_e32 v36, v37, v38
	v_fmac_f32_e32 v41, v32, v32
	v_fmac_f32_e32 v42, v34, v34
	v_add_f32_e32 v37, v39, v40
	v_add_f32_e32 v19, v19, v36
	v_add_f32_e32 v38, v41, v42
	v_add_f32_e32 v19, v19, v37
	v_add_f32_e32 v19, v19, v38
	ds_bpermute_b32 v36, v1, v19
	s_waitcnt lgkmcnt(0)
	v_add_f32_e32 v19, v19, v36
	ds_bpermute_b32 v44, v12, v19
	global_load_dwordx4 v[36:39], v[2:3], off
	global_load_dwordx4 v[40:43], v[2:3], off offset:1024
	s_waitcnt lgkmcnt(0)
	v_add_f32_e32 v19, v19, v44
	ds_bpermute_b32 v48, v13, v19
	global_load_dwordx4 v[44:47], v[2:3], off offset:2048
	s_waitcnt lgkmcnt(0)
	v_add_f32_e32 v19, v19, v48
	global_load_dwordx4 v[48:51], v[2:3], off offset:3072
	ds_bpermute_b32 v52, v14, v19
	s_waitcnt lgkmcnt(0)
	v_add_f32_e32 v19, v19, v52
	ds_bpermute_b32 v52, v15, v19
	s_waitcnt lgkmcnt(0)
	v_add_f32_e32 v19, v19, v52
	ds_bpermute_b32 v52, v16, v19
	s_waitcnt lgkmcnt(0)
	v_add_f32_e32 v19, v19, v52
	v_fmamk_f32 v19, v19, 0x3a800000, v17
	v_mul_f32_e32 v52, 0x4f800000, v19
	v_cmp_gt_f32_e32 vcc, s1, v19
	s_nop 1
	v_cndmask_b32_e32 v19, v19, v52, vcc
	v_sqrt_f32_e32 v52, v19
	s_nop 0
	v_add_u32_e32 v53, -1, v52
	v_add_u32_e32 v54, 1, v52
	v_fma_f32 v55, -v53, v52, v19
	v_fma_f32 v56, -v54, v52, v19
	v_cmp_ge_f32_e64 s[4:5], 0, v55
	s_nop 1
	v_cndmask_b32_e64 v52, v52, v53, s[4:5]
	v_cmp_lt_f32_e64 s[4:5], 0, v56
	s_nop 1
	v_cndmask_b32_e64 v52, v52, v54, s[4:5]
	v_mul_f32_e32 v53, 0x37800000, v52
	v_cndmask_b32_e32 v52, v52, v53, vcc
	v_cmp_class_f32_e32 vcc, v19, v18
	s_nop 1
	v_cndmask_b32_e32 v19, v52, v19, vcc
	v_div_scale_f32 v54, s[4:5], v19, v19, 1.0
	v_rcp_f32_e32 v55, v54
	v_div_scale_f32 v56, vcc, 1.0, v19, 1.0
	v_lshl_add_u64 v[52:53], v[6:7], 0, s[14:15]
	v_fma_f32 v57, -v54, v55, 1.0
	v_fmac_f32_e32 v55, v57, v55
	v_mul_f32_e32 v57, v56, v55
	v_fma_f32 v58, -v54, v57, v56
	v_fmac_f32_e32 v57, v58, v55
	v_fma_f32 v54, -v54, v57, v56
	v_div_fmas_f32 v54, v54, v55, v57
	v_div_fixup_f32 v19, v54, v19, 1.0
	v_mul_f32_e32 v20, v20, v19
	v_mul_f32_e32 v22, v22, v19
	v_mul_f32_e32 v21, v21, v19
	v_mul_f32_e32 v23, v23, v19
	v_mul_f32_e32 v24, v24, v19
	v_mul_f32_e32 v26, v26, v19
	v_mul_f32_e32 v28, v28, v19
	v_mul_f32_e32 v30, v30, v19
	s_waitcnt vmcnt(3)
	v_mul_f32_e32 v20, v36, v20
	v_mul_f32_e32 v22, v38, v22
	v_mul_f32_e32 v25, v25, v19
	v_mul_f32_e32 v27, v27, v19
	v_mul_f32_e32 v29, v29, v19
	v_mul_f32_e32 v31, v31, v19
	v_mul_f32_e32 v32, v32, v19
	v_mul_f32_e32 v33, v33, v19
	v_mul_f32_e32 v34, v34, v19
	v_mul_f32_e32 v19, v35, v19
	v_mul_f32_e32 v21, v37, v21
	v_mul_f32_e32 v23, v39, v23
	s_waitcnt vmcnt(2)
	v_mul_f32_e32 v24, v40, v24
	v_mul_f32_e32 v26, v42, v26
	s_waitcnt vmcnt(1)
	v_mul_f32_e32 v28, v44, v28
	v_mul_f32_e32 v30, v46, v30
	v_bfe_u32 v35, v20, 16, 1
	v_bfe_u32 v37, v22, 16, 1
	v_mul_f32_e32 v25, v41, v25
	v_mul_f32_e32 v27, v43, v27
	v_mul_f32_e32 v29, v45, v29
	v_mul_f32_e32 v31, v47, v31
	v_bfe_u32 v36, v21, 16, 1
	v_bfe_u32 v38, v23, 16, 1
	v_bfe_u32 v39, v24, 16, 1
	v_bfe_u32 v41, v26, 16, 1
	v_bfe_u32 v43, v28, 16, 1
	v_bfe_u32 v45, v30, 16, 1
	v_add3_u32 v20, v20, v35, s3
	v_add3_u32 v22, v22, v37, s3
	s_waitcnt vmcnt(0)
	v_mul_f32_e32 v32, v32, v48
	v_mul_f32_e32 v34, v34, v50
	v_bfe_u32 v40, v25, 16, 1
	v_bfe_u32 v42, v27, 16, 1
	v_bfe_u32 v44, v29, 16, 1
	v_bfe_u32 v46, v31, 16, 1
	v_add3_u32 v21, v21, v36, s3
	v_add3_u32 v23, v23, v38, s3
	v_add3_u32 v24, v24, v39, s3
	v_add3_u32 v26, v26, v41, s3
	v_add3_u32 v28, v28, v43, s3
	v_add3_u32 v30, v30, v45, s3
	v_lshrrev_b32_e32 v20, 16, v20
	v_lshrrev_b32_e32 v22, 16, v22
	v_mul_f32_e32 v33, v33, v49
	v_mul_f32_e32 v19, v19, v51
	v_bfe_u32 v47, v32, 16, 1
	v_bfe_u32 v49, v34, 16, 1
	v_add3_u32 v25, v25, v40, s3
	v_add3_u32 v27, v27, v42, s3
	v_add3_u32 v29, v29, v44, s3
	v_add3_u32 v31, v31, v46, s3
	v_lshrrev_b32_e32 v24, 16, v24
	v_lshrrev_b32_e32 v26, 16, v26
	v_lshrrev_b32_e32 v28, 16, v28
	v_lshrrev_b32_e32 v30, 16, v30
	v_and_or_b32 v20, v21, s13, v20
	v_and_or_b32 v21, v23, s13, v22
	v_bfe_u32 v48, v33, 16, 1
	v_add3_u32 v32, v32, v47, s3
	v_add3_u32 v34, v34, v49, s3
	v_and_or_b32 v22, v25, s13, v24
	v_and_or_b32 v23, v27, s13, v26
	v_and_or_b32 v24, v29, s13, v28
	v_and_or_b32 v25, v31, s13, v30
	global_store_dwordx2 v[52:53], v[20:21], off
	global_store_dwordx2 v[52:53], v[22:23], off offset:512
	global_store_dwordx2 v[52:53], v[24:25], off offset:1024
	v_bfe_u32 v20, v19, 16, 1
	v_add3_u32 v33, v33, v48, s3
	v_lshrrev_b32_e32 v32, 16, v32
	v_lshrrev_b32_e32 v34, 16, v34
	v_add3_u32 v19, v19, v20, s3
	v_and_or_b32 v26, v33, s13, v32
	v_and_or_b32 v27, v19, s13, v34
	global_store_dwordx2 v[52:53], v[26:27], off offset:1536
	s_add_i32 s4, s11, s0
	s_cmpk_gt_i32 s4, 0x3fff
	s_cbranch_scc0 .LBB0_35

.LBB0_35:
	s_ashr_i32 s5, s4, 31
	s_lshl_b64 s[14:15], s[4:5], 12
	v_lshl_add_u64 v[32:33], v[4:5], 0, s[14:15]
	global_load_dwordx4 v[20:23], v[32:33], off nt
	global_load_dwordx4 v[24:27], v[32:33], off offset:1024 nt
	global_load_dwordx4 v[28:31], v[32:33], off offset:2048 nt
	s_nop 0
	global_load_dwordx4 v[32:35], v[32:33], off offset:3072 nt
	s_lshl_b64 s[14:15], s[4:5], 11
	s_waitcnt vmcnt(3)
	v_mul_f32_e32 v19, v21, v21
	v_mul_f32_e32 v36, v23, v23
	s_waitcnt vmcnt(2)
	v_mul_f32_e32 v37, v25, v25
	v_mul_f32_e32 v38, v27, v27
	s_waitcnt vmcnt(1)
	v_mul_f32_e32 v39, v29, v29
	v_mul_f32_e32 v40, v31, v31
	v_fmac_f32_e32 v19, v20, v20
	v_fmac_f32_e32 v36, v22, v22
	v_fmac_f32_e32 v37, v24, v24
	v_fmac_f32_e32 v38, v26, v26
	s_waitcnt vmcnt(0)
	v_mul_f32_e32 v41, v33, v33
	v_mul_f32_e32 v42, v35, v35
	v_fmac_f32_e32 v39, v28, v28
	v_fmac_f32_e32 v40, v30, v30
	v_add_f32_e32 v19, v19, v36
	v_add_f32_e32 v36, v37, v38
	v_fmac_f32_e32 v41, v32, v32
	v_fmac_f32_e32 v42, v34, v34
	v_add_f32_e32 v37, v39, v40
	v_add_f32_e32 v19, v19, v36
	v_add_f32_e32 v38, v41, v42
	v_add_f32_e32 v19, v19, v37
	v_add_f32_e32 v19, v19, v38
	ds_bpermute_b32 v36, v1, v19
	s_waitcnt lgkmcnt(0)
	v_add_f32_e32 v19, v19, v36
	ds_bpermute_b32 v44, v12, v19
	global_load_dwordx4 v[36:39], v[2:3], off
	global_load_dwordx4 v[40:43], v[2:3], off offset:1024
	s_waitcnt lgkmcnt(0)
	v_add_f32_e32 v19, v19, v44
	ds_bpermute_b32 v48, v13, v19
	global_load_dwordx4 v[44:47], v[2:3], off offset:2048
	s_waitcnt lgkmcnt(0)
	v_add_f32_e32 v19, v19, v48
	global_load_dwordx4 v[48:51], v[2:3], off offset:3072
	ds_bpermute_b32 v52, v14, v19
	s_waitcnt lgkmcnt(0)
	v_add_f32_e32 v19, v19, v52
	ds_bpermute_b32 v52, v15, v19
	s_waitcnt lgkmcnt(0)
	v_add_f32_e32 v19, v19, v52
	ds_bpermute_b32 v52, v16, v19
	s_waitcnt lgkmcnt(0)
	v_add_f32_e32 v19, v19, v52
	v_fmamk_f32 v19, v19, 0x3a800000, v17
	v_mul_f32_e32 v52, 0x4f800000, v19
	v_cmp_gt_f32_e32 vcc, s1, v19
	s_nop 1
	v_cndmask_b32_e32 v19, v19, v52, vcc
	v_sqrt_f32_e32 v52, v19
	s_nop 0
	v_add_u32_e32 v53, -1, v52
	v_add_u32_e32 v54, 1, v52
	v_fma_f32 v55, -v53, v52, v19
	v_fma_f32 v56, -v54, v52, v19
	v_cmp_ge_f32_e64 s[4:5], 0, v55
	s_nop 1
	v_cndmask_b32_e64 v52, v52, v53, s[4:5]
	v_cmp_lt_f32_e64 s[4:5], 0, v56
	s_nop 1
	v_cndmask_b32_e64 v52, v52, v54, s[4:5]
	v_mul_f32_e32 v53, 0x37800000, v52
	v_cndmask_b32_e32 v52, v52, v53, vcc
	v_cmp_class_f32_e32 vcc, v19, v18
	s_nop 1
	v_cndmask_b32_e32 v19, v52, v19, vcc
	v_div_scale_f32 v54, s[4:5], v19, v19, 1.0
	v_rcp_f32_e32 v55, v54
	v_div_scale_f32 v56, vcc, 1.0, v19, 1.0
	v_lshl_add_u64 v[52:53], v[6:7], 0, s[14:15]
	v_fma_f32 v57, -v54, v55, 1.0
	v_fmac_f32_e32 v55, v57, v55
	v_mul_f32_e32 v57, v56, v55
	v_fma_f32 v58, -v54, v57, v56
	v_fmac_f32_e32 v57, v58, v55
	v_fma_f32 v54, -v54, v57, v56
	v_div_fmas_f32 v54, v54, v55, v57
	v_div_fixup_f32 v19, v54, v19, 1.0
	v_mul_f32_e32 v20, v20, v19
	v_mul_f32_e32 v22, v22, v19
	v_mul_f32_e32 v21, v21, v19
	v_mul_f32_e32 v23, v23, v19
	v_mul_f32_e32 v24, v24, v19
	v_mul_f32_e32 v26, v26, v19
	v_mul_f32_e32 v28, v28, v19
	v_mul_f32_e32 v30, v30, v19
	s_waitcnt vmcnt(3)
	v_mul_f32_e32 v20, v36, v20
	v_mul_f32_e32 v22, v38, v22
	v_mul_f32_e32 v25, v25, v19
	v_mul_f32_e32 v27, v27, v19
	v_mul_f32_e32 v29, v29, v19
	v_mul_f32_e32 v31, v31, v19
	v_mul_f32_e32 v32, v32, v19
	v_mul_f32_e32 v33, v33, v19
	v_mul_f32_e32 v34, v34, v19
	v_mul_f32_e32 v19, v35, v19
	v_mul_f32_e32 v21, v37, v21
	v_mul_f32_e32 v23, v39, v23
	s_waitcnt vmcnt(2)
	v_mul_f32_e32 v24, v40, v24
	v_mul_f32_e32 v26, v42, v26
	s_waitcnt vmcnt(1)
	v_mul_f32_e32 v28, v44, v28
	v_mul_f32_e32 v30, v46, v30
	v_bfe_u32 v35, v20, 16, 1
	v_bfe_u32 v37, v22, 16, 1
	v_mul_f32_e32 v25, v41, v25
	v_mul_f32_e32 v27, v43, v27
	v_mul_f32_e32 v29, v45, v29
	v_mul_f32_e32 v31, v47, v31
	v_bfe_u32 v36, v21, 16, 1
	v_bfe_u32 v38, v23, 16, 1
	v_bfe_u32 v39, v24, 16, 1
	v_bfe_u32 v41, v26, 16, 1
	v_bfe_u32 v43, v28, 16, 1
	v_bfe_u32 v45, v30, 16, 1
	v_add3_u32 v20, v20, v35, s3
	v_add3_u32 v22, v22, v37, s3
	s_waitcnt vmcnt(0)
	v_mul_f32_e32 v32, v32, v48
	v_mul_f32_e32 v34, v34, v50
	v_bfe_u32 v40, v25, 16, 1
	v_bfe_u32 v42, v27, 16, 1
	v_bfe_u32 v44, v29, 16, 1
	v_bfe_u32 v46, v31, 16, 1
	v_add3_u32 v21, v21, v36, s3
	v_add3_u32 v23, v23, v38, s3
	v_add3_u32 v24, v24, v39, s3
	v_add3_u32 v26, v26, v41, s3
	v_add3_u32 v28, v28, v43, s3
	v_add3_u32 v30, v30, v45, s3
	v_lshrrev_b32_e32 v20, 16, v20
	v_lshrrev_b32_e32 v22, 16, v22
	v_mul_f32_e32 v33, v33, v49
	v_mul_f32_e32 v19, v19, v51
	v_bfe_u32 v47, v32, 16, 1
	v_bfe_u32 v49, v34, 16, 1
	v_add3_u32 v25, v25, v40, s3
	v_add3_u32 v27, v27, v42, s3
	v_add3_u32 v29, v29, v44, s3
	v_add3_u32 v31, v31, v46, s3
	v_lshrrev_b32_e32 v24, 16, v24
	v_lshrrev_b32_e32 v26, 16, v26
	v_lshrrev_b32_e32 v28, 16, v28
	v_lshrrev_b32_e32 v30, 16, v30
	v_and_or_b32 v20, v21, s13, v20
	v_and_or_b32 v21, v23, s13, v22
	v_bfe_u32 v48, v33, 16, 1
	v_add3_u32 v32, v32, v47, s3
	v_add3_u32 v34, v34, v49, s3
	v_and_or_b32 v22, v25, s13, v24
	v_and_or_b32 v23, v27, s13, v26
	v_and_or_b32 v24, v29, s13, v28
	v_and_or_b32 v25, v31, s13, v30
	global_store_dwordx2 v[52:53], v[20:21], off
	global_store_dwordx2 v[52:53], v[22:23], off offset:512
	global_store_dwordx2 v[52:53], v[24:25], off offset:1024
	v_bfe_u32 v20, v19, 16, 1
	v_add3_u32 v33, v33, v48, s3
	v_lshrrev_b32_e32 v32, 16, v32
	v_lshrrev_b32_e32 v34, 16, v34
	v_add3_u32 v19, v19, v20, s3
	v_and_or_b32 v26, v33, s13, v32
	v_and_or_b32 v27, v19, s13, v34
	global_store_dwordx2 v[52:53], v[26:27], off offset:1536
	s_add_i32 s4, s12, s0
	s_cmpk_gt_i32 s4, 0x3fff
	s_cbranch_scc1 .LBB0_30
.LBB0_36:
	s_ashr_i32 s5, s4, 31
	s_lshl_b64 s[14:15], s[4:5], 12
	v_lshl_add_u64 v[32:33], v[4:5], 0, s[14:15]
	global_load_dwordx4 v[20:23], v[32:33], off nt
	global_load_dwordx4 v[24:27], v[32:33], off offset:1024 nt
	global_load_dwordx4 v[28:31], v[32:33], off offset:2048 nt
	s_nop 0
	global_load_dwordx4 v[32:35], v[32:33], off offset:3072 nt
	s_lshl_b64 s[14:15], s[4:5], 11
	s_waitcnt vmcnt(3)
	v_mul_f32_e32 v19, v21, v21
	v_mul_f32_e32 v36, v23, v23
	s_waitcnt vmcnt(2)
	v_mul_f32_e32 v37, v25, v25
	v_mul_f32_e32 v38, v27, v27
	s_waitcnt vmcnt(1)
	v_mul_f32_e32 v39, v29, v29
	v_mul_f32_e32 v40, v31, v31
	v_fmac_f32_e32 v19, v20, v20
	v_fmac_f32_e32 v36, v22, v22
	v_fmac_f32_e32 v37, v24, v24
	v_fmac_f32_e32 v38, v26, v26
	s_waitcnt vmcnt(0)
	v_mul_f32_e32 v41, v33, v33
	v_mul_f32_e32 v42, v35, v35
	v_fmac_f32_e32 v39, v28, v28
	v_fmac_f32_e32 v40, v30, v30
	v_add_f32_e32 v19, v19, v36
	v_add_f32_e32 v36, v37, v38
	v_fmac_f32_e32 v41, v32, v32
	v_fmac_f32_e32 v42, v34, v34
	v_add_f32_e32 v37, v39, v40
	v_add_f32_e32 v19, v19, v36
	v_add_f32_e32 v38, v41, v42
	v_add_f32_e32 v19, v19, v37
	v_add_f32_e32 v19, v19, v38
	ds_bpermute_b32 v36, v1, v19
	s_waitcnt lgkmcnt(0)
	v_add_f32_e32 v19, v19, v36
	ds_bpermute_b32 v44, v12, v19
	global_load_dwordx4 v[36:39], v[2:3], off
	global_load_dwordx4 v[40:43], v[2:3], off offset:1024
	s_waitcnt lgkmcnt(0)
	v_add_f32_e32 v19, v19, v44
	ds_bpermute_b32 v48, v13, v19
	global_load_dwordx4 v[44:47], v[2:3], off offset:2048
	s_waitcnt lgkmcnt(0)
	v_add_f32_e32 v19, v19, v48
	global_load_dwordx4 v[48:51], v[2:3], off offset:3072
	ds_bpermute_b32 v52, v14, v19
	s_waitcnt lgkmcnt(0)
	v_add_f32_e32 v19, v19, v52
	ds_bpermute_b32 v52, v15, v19
	s_waitcnt lgkmcnt(0)
	v_add_f32_e32 v19, v19, v52
	ds_bpermute_b32 v52, v16, v19
	s_waitcnt lgkmcnt(0)
	v_add_f32_e32 v19, v19, v52
	v_fmamk_f32 v19, v19, 0x3a800000, v17
	v_mul_f32_e32 v52, 0x4f800000, v19
	v_cmp_gt_f32_e32 vcc, s1, v19
	s_nop 1
	v_cndmask_b32_e32 v19, v19, v52, vcc
	v_sqrt_f32_e32 v52, v19
	s_nop 0
	v_add_u32_e32 v53, -1, v52
	v_add_u32_e32 v54, 1, v52
	v_fma_f32 v55, -v53, v52, v19
	v_fma_f32 v56, -v54, v52, v19
	v_cmp_ge_f32_e64 s[4:5], 0, v55
	s_nop 1
	v_cndmask_b32_e64 v52, v52, v53, s[4:5]
	v_cmp_lt_f32_e64 s[4:5], 0, v56
	s_nop 1
	v_cndmask_b32_e64 v52, v52, v54, s[4:5]
	v_mul_f32_e32 v53, 0x37800000, v52
	v_cndmask_b32_e32 v52, v52, v53, vcc
	v_cmp_class_f32_e32 vcc, v19, v18
	s_nop 1
	v_cndmask_b32_e32 v19, v52, v19, vcc
	v_div_scale_f32 v54, s[4:5], v19, v19, 1.0
	v_rcp_f32_e32 v55, v54
	v_div_scale_f32 v56, vcc, 1.0, v19, 1.0
	v_lshl_add_u64 v[52:53], v[6:7], 0, s[14:15]
	v_fma_f32 v57, -v54, v55, 1.0
	v_fmac_f32_e32 v55, v57, v55
	v_mul_f32_e32 v57, v56, v55
	v_fma_f32 v58, -v54, v57, v56
	v_fmac_f32_e32 v57, v58, v55
	v_fma_f32 v54, -v54, v57, v56
	v_div_fmas_f32 v54, v54, v55, v57
	v_div_fixup_f32 v19, v54, v19, 1.0
	v_mul_f32_e32 v20, v20, v19
	v_mul_f32_e32 v22, v22, v19
	v_mul_f32_e32 v21, v21, v19
	v_mul_f32_e32 v23, v23, v19
	v_mul_f32_e32 v24, v24, v19
	v_mul_f32_e32 v26, v26, v19
	v_mul_f32_e32 v28, v28, v19
	v_mul_f32_e32 v30, v30, v19
	s_waitcnt vmcnt(3)
	v_mul_f32_e32 v20, v36, v20
	v_mul_f32_e32 v22, v38, v22
	v_mul_f32_e32 v25, v25, v19
	v_mul_f32_e32 v27, v27, v19
	v_mul_f32_e32 v29, v29, v19
	v_mul_f32_e32 v31, v31, v19
	v_mul_f32_e32 v32, v32, v19
	v_mul_f32_e32 v33, v33, v19
	v_mul_f32_e32 v34, v34, v19
	v_mul_f32_e32 v19, v35, v19
	v_mul_f32_e32 v21, v37, v21
	v_mul_f32_e32 v23, v39, v23
	s_waitcnt vmcnt(2)
	v_mul_f32_e32 v24, v40, v24
	v_mul_f32_e32 v26, v42, v26
	s_waitcnt vmcnt(1)
	v_mul_f32_e32 v28, v44, v28
	v_mul_f32_e32 v30, v46, v30
	v_bfe_u32 v35, v20, 16, 1
	v_bfe_u32 v37, v22, 16, 1
	v_mul_f32_e32 v25, v41, v25
	v_mul_f32_e32 v27, v43, v27
	v_mul_f32_e32 v29, v45, v29
	v_mul_f32_e32 v31, v47, v31
	v_bfe_u32 v36, v21, 16, 1
	v_bfe_u32 v38, v23, 16, 1
	v_bfe_u32 v39, v24, 16, 1
	v_bfe_u32 v41, v26, 16, 1
	v_bfe_u32 v43, v28, 16, 1
	v_bfe_u32 v45, v30, 16, 1
	v_add3_u32 v20, v20, v35, s3
	v_add3_u32 v22, v22, v37, s3
	s_waitcnt vmcnt(0)
	v_mul_f32_e32 v32, v32, v48
	v_mul_f32_e32 v34, v34, v50
	v_bfe_u32 v40, v25, 16, 1
	v_bfe_u32 v42, v27, 16, 1
	v_bfe_u32 v44, v29, 16, 1
	v_bfe_u32 v46, v31, 16, 1
	v_add3_u32 v21, v21, v36, s3
	v_add3_u32 v23, v23, v38, s3
	v_add3_u32 v24, v24, v39, s3
	v_add3_u32 v26, v26, v41, s3
	v_add3_u32 v28, v28, v43, s3
	v_add3_u32 v30, v30, v45, s3
	v_lshrrev_b32_e32 v20, 16, v20
	v_lshrrev_b32_e32 v22, 16, v22
	v_mul_f32_e32 v33, v33, v49
	v_mul_f32_e32 v19, v19, v51
	v_bfe_u32 v47, v32, 16, 1
	v_bfe_u32 v49, v34, 16, 1
	v_add3_u32 v25, v25, v40, s3
	v_add3_u32 v27, v27, v42, s3
	v_add3_u32 v29, v29, v44, s3
	v_add3_u32 v31, v31, v46, s3
	v_lshrrev_b32_e32 v24, 16, v24
	v_lshrrev_b32_e32 v26, 16, v26
	v_lshrrev_b32_e32 v28, 16, v28
	v_lshrrev_b32_e32 v30, 16, v30
	v_and_or_b32 v20, v21, s13, v20
	v_and_or_b32 v21, v23, s13, v22
	v_bfe_u32 v48, v33, 16, 1
	v_add3_u32 v32, v32, v47, s3
	v_add3_u32 v34, v34, v49, s3
	v_and_or_b32 v22, v25, s13, v24
	v_and_or_b32 v23, v27, s13, v26
	v_and_or_b32 v24, v29, s13, v28
	v_and_or_b32 v25, v31, s13, v30
	global_store_dwordx2 v[52:53], v[20:21], off
	global_store_dwordx2 v[52:53], v[22:23], off offset:512
	global_store_dwordx2 v[52:53], v[24:25], off offset:1024
	v_bfe_u32 v20, v19, 16, 1
	v_add3_u32 v33, v33, v48, s3
	v_lshrrev_b32_e32 v32, 16, v32
	v_lshrrev_b32_e32 v34, 16, v34
	v_add3_u32 v19, v19, v20, s3
	v_and_or_b32 v26, v33, s13, v32
	v_and_or_b32 v27, v19, s13, v34
	global_store_dwordx2 v[52:53], v[26:27], off offset:1536
	s_branch .LBB0_30
